# v9 + ticket prefetch also in the score, lrux and lruy work-queue loops
# baseline (speedup 1.0000x reference)
; #define LAS __attribute__((address_space(3)))
; __device__ __forceinline__ int fresh_lane() { int ln; asm volatile("v_mbcnt_lo_u32_b32 %0, -1, 0\n\tv_mbcnt_hi_u32_b32 %0, -1, %0" : "=v"(ln)); return ln; }
; __device__ __forceinline__ int q_block(const Frame& F, int cw) {
;     volatile LAS int* slot = (volatile LAS int*)(F.lds + LDS_MISC + 64);
;     __syncthreads();
;     if (F.wave == 0 && fresh_lane() == 0) *slot = (int)__hip_atomic_fetch_add(F.ctl + cw, 1u, __ATOMIC_RELAXED, __HIP_MEMORY_SCOPE_AGENT);
;     __syncthreads();
;     return *slot;
; }
; template <unsigned MASK> __global__ void __launch_bounds__(NTHREADS, 2) fwd(Args A0) {
;     ...
;             for (int sr = 0; sr < SUBREP(0); ++sr) { for (int u = q_block(F, cwb + 0 + 2048 * sr); u < (1024 + 160); u = q_block(F, cwb + 0 + 2048 * sr)) {
;                 if (sr > 0) continue;
;                 if (u < 1024) { const int b = u >> 9, c = 63 - ((u >> 3) & 63), kc = u & 7; if (c >= 4 && kc < sel_nchunks(0, c)) score_item(F, l, 0, b, c, kc); }
;                 else { const int v = u - 1024; score_item(F, l, 1, v / 5, 0, v % 5); } } }
.LBB0_832:
	s_cmp_eq_u64 s[48:49], 0
	s_cbranch_scc1 .Lq_score_top
	s_mov_b64 s[100:101], exec
	s_mov_b64 exec, 1
	v_mov_b32_e32 v140, 1
	global_atomic_add v140, v201, v140, s[0:1] sc0
	s_mov_b64 exec, s[100:101]

; #define LAS __attribute__((address_space(3)))
; __device__ __forceinline__ int fresh_lane() { int ln; asm volatile("v_mbcnt_lo_u32_b32 %0, -1, 0\n\tv_mbcnt_hi_u32_b32 %0, -1, %0" : "=v"(ln)); return ln; }
; __device__ __forceinline__ int q_block(const Frame& F, int cw) {
;     volatile LAS int* slot = (volatile LAS int*)(F.lds + LDS_MISC + 64);
;     __syncthreads();
;     if (F.wave == 0 && fresh_lane() == 0) *slot = (int)__hip_atomic_fetch_add(F.ctl + cw, 1u, __ATOMIC_RELAXED, __HIP_MEMORY_SCOPE_AGENT);
;     __syncthreads();
;     return *slot;
; }
; template <unsigned MASK> __global__ void __launch_bounds__(NTHREADS, 2) fwd(Args A0) {
;     ...
;             for (int sr = 0; sr < SUBREP(0); ++sr) { for (int u = q_block(F, cwb + 0 + 2048 * sr); u < (1024 + 160); u = q_block(F, cwb + 0 + 2048 * sr)) {
;                 if (sr > 0) continue;
;                 if (u < 1024) { const int b = u >> 9, c = 63 - ((u >> 3) & 63), kc = u & 7; if (c >= 4 && kc < sel_nchunks(0, c)) score_item(F, l, 0, b, c, kc); }
;                 else { const int v = u - 1024; score_item(F, l, 1, v / 5, 0, v % 5); } } }
.LBB0_886:
	s_or_b64 exec, exec, s[6:7]
	s_andn2_b64 vcc, exec, s[48:49]
	s_barrier
	s_cbranch_vccnz .LBB0_831
	s_waitcnt vmcnt(0)
	v_readfirstlane_b32 s4, v140
	v_mov_b32_e32 v1, s87
	s_nop 0
	v_mov_b32_e32 v0, s4
	ds_write_b32 v1, v0
	s_branch .LBB0_831

; #define LAS __attribute__((address_space(3)))
; __device__ __forceinline__ int fresh_lane() { int ln; asm volatile("v_mbcnt_lo_u32_b32 %0, -1, 0\n\tv_mbcnt_hi_u32_b32 %0, -1, %0" : "=v"(ln)); return ln; }
; __device__ __forceinline__ int q_block(const Frame& F, int cw) {
;     volatile LAS int* slot = (volatile LAS int*)(F.lds + LDS_MISC + 64);
;     __syncthreads();
;     if (F.wave == 0 && fresh_lane() == 0) *slot = (int)__hip_atomic_fetch_add(F.ctl + cw, 1u, __ATOMIC_RELAXED, __HIP_MEMORY_SCOPE_AGENT);
;     __syncthreads();
;     return *slot;
; }
; template <unsigned MASK> __global__ void __launch_bounds__(NTHREADS, 2) fwd(Args A0) {
;     ...
;             for (int sr = 0; sr < SUBREP(3); ++sr) { for (int u = q_block(F, cwb + 192 + 2048 * sr); u < (512); u = q_block(F, cwb + 192 + 2048 * sr)) { const int b = u >> 8, c = (u >> 2) & 63, nn = u & 3;
;                 lru_pair<false>(F, l, 0, b, c, 4 * nn); lru_pair<false>(F, l, 0, b, c, 4 * nn + 2); } }
.LBB0_1229:
	s_cmp_eq_u64 s[48:49], 0
	s_cbranch_scc1 .Lq_lrux_top
	s_mov_b64 s[100:101], exec
	s_mov_b64 exec, 1
	v_mov_b32_e32 v140, 1
	global_atomic_add v140, v201, v140, s[18:19] sc0
	s_mov_b64 exec, s[100:101]

; #define LAS __attribute__((address_space(3)))
; __device__ __forceinline__ int fresh_lane() { int ln; asm volatile("v_mbcnt_lo_u32_b32 %0, -1, 0\n\tv_mbcnt_hi_u32_b32 %0, -1, %0" : "=v"(ln)); return ln; }
; __device__ __forceinline__ int q_block(const Frame& F, int cw) {
;     volatile LAS int* slot = (volatile LAS int*)(F.lds + LDS_MISC + 64);
;     __syncthreads();
;     if (F.wave == 0 && fresh_lane() == 0) *slot = (int)__hip_atomic_fetch_add(F.ctl + cw, 1u, __ATOMIC_RELAXED, __HIP_MEMORY_SCOPE_AGENT);
;     __syncthreads();
;     return *slot;
; }
; template <unsigned MASK> __global__ void __launch_bounds__(NTHREADS, 2) fwd(Args A0) {
;     ...
;             for (int sr = 0; sr < SUBREP(3); ++sr) { for (int u = q_block(F, cwb + 192 + 2048 * sr); u < (512); u = q_block(F, cwb + 192 + 2048 * sr)) { const int b = u >> 8, c = (u >> 2) & 63, nn = u & 3;
;                 lru_pair<false>(F, l, 0, b, c, 4 * nn); lru_pair<false>(F, l, 0, b, c, 4 * nn + 2); } }
.LBB0_1241:
	s_andn2_b64 vcc, exec, s[48:49]
	s_barrier
	s_barrier
	s_cbranch_vccnz .LBB0_1228
	s_waitcnt vmcnt(0)
	v_readfirstlane_b32 s4, v140
	v_mov_b32_e32 v1, s87
	s_nop 0
	v_mov_b32_e32 v0, s4
	ds_write_b32 v1, v0
	s_branch .LBB0_1228

; #define LAS __attribute__((address_space(3)))
; __device__ __forceinline__ int fresh_lane() { int ln; asm volatile("v_mbcnt_lo_u32_b32 %0, -1, 0\n\tv_mbcnt_hi_u32_b32 %0, -1, %0" : "=v"(ln)); return ln; }
; __device__ __forceinline__ int q_block(const Frame& F, int cw) {
;     volatile LAS int* slot = (volatile LAS int*)(F.lds + LDS_MISC + 64);
;     __syncthreads();
;     if (F.wave == 0 && fresh_lane() == 0) *slot = (int)__hip_atomic_fetch_add(F.ctl + cw, 1u, __ATOMIC_RELAXED, __HIP_MEMORY_SCOPE_AGENT);
;     __syncthreads();
;     return *slot;
; }
; template <unsigned MASK> __global__ void __launch_bounds__(NTHREADS, 2) fwd(Args A0) {
;     ...
;             for (int sr = 0; sr < SUBREP(5); ++sr) { for (int u = q_block(F, cwb + 320 + 2048 * sr); u < (640); u = q_block(F, cwb + 320 + 2048 * sr)) {
;                 int samp, b, c, nn; if (u < 512) { samp = 0; b = u >> 8; c = (u >> 2) & 63; nn = u & 3; } else { const int v = u - 512; samp = 1; b = v >> 2; c = 0; nn = v & 3; }
;                 lru_pair<true>(F, l, samp, b, c, 4 * nn); lru_pair<true>(F, l, samp, b, c, 4 * nn + 2); } }
.LBB0_1580:
	s_cmp_eq_u64 s[34:35], 0
	s_cbranch_scc1 .Lq_lruy_top
	s_mov_b64 s[100:101], exec
	s_mov_b64 exec, 1
	v_mov_b32_e32 v170, 1
	global_atomic_add v170, v201, v170, s[36:37] sc0
	s_mov_b64 exec, s[100:101]

; #define LAS __attribute__((address_space(3)))
; __device__ __forceinline__ int fresh_lane() { int ln; asm volatile("v_mbcnt_lo_u32_b32 %0, -1, 0\n\tv_mbcnt_hi_u32_b32 %0, -1, %0" : "=v"(ln)); return ln; }
; __device__ __forceinline__ int q_block(const Frame& F, int cw) {
;     volatile LAS int* slot = (volatile LAS int*)(F.lds + LDS_MISC + 64);
;     __syncthreads();
;     if (F.wave == 0 && fresh_lane() == 0) *slot = (int)__hip_atomic_fetch_add(F.ctl + cw, 1u, __ATOMIC_RELAXED, __HIP_MEMORY_SCOPE_AGENT);
;     __syncthreads();
;     return *slot;
; }
; template <unsigned MASK> __global__ void __launch_bounds__(NTHREADS, 2) fwd(Args A0) {
;     ...
;             for (int sr = 0; sr < SUBREP(5); ++sr) { for (int u = q_block(F, cwb + 320 + 2048 * sr); u < (640); u = q_block(F, cwb + 320 + 2048 * sr)) {
;                 int samp, b, c, nn; if (u < 512) { samp = 0; b = u >> 8; c = (u >> 2) & 63; nn = u & 3; } else { const int v = u - 512; samp = 1; b = v >> 2; c = 0; nn = v & 3; }
;                 lru_pair<true>(F, l, samp, b, c, 4 * nn); lru_pair<true>(F, l, samp, b, c, 4 * nn + 2); } }
.LBB0_1726:
	s_andn2_b64 vcc, exec, s[34:35]
	v_readlane_b32 s87, v254, 20
	s_barrier
	s_barrier
	s_cbranch_vccnz .LBB0_1579
	s_waitcnt vmcnt(0)
	v_readfirstlane_b32 s4, v170
	v_mov_b32_e32 v1, s87
	s_nop 0
	v_mov_b32_e32 v0, s4
	ds_write_b32 v1, v0
	s_branch .LBB0_1579
